# attention K/V tile loads: 32-bit row offset + scalar tile base (saddr form) instead of 64-bit v_mad_u64_u32 with SGPR carry-out
# speedup vs baseline: 1.0023x; 1.0008x over previous
; __device__ __forceinline__ void attn_load1(const bf16_t* __restrict__ src, int ld, int t, u32x4 (&r)[2]) {
;     const int tid = threadIdx.x;
; #pragma unroll
;     for (int i = 0; i < 2; ++i) {
;         const int c = tid + NTHR * i, key = c >> 4, ch = c & 15;
;         r[i] = *(const u32x4*)(src + (size_t)(t * 64 + key) * ld + ch * 8);
;     }
; template <int NS>
; __device__ __forceinline__ void attn_unit(const AUnit& u, unsigned char* lds, const bf16_t* __restrict__ GT, bf16_t* BRc, float sc, float lam, const float* __restrict__ subln) {
;     ...
;     f32x16 O0[4], O1[4];
;     float m0 = -1e30f, m1 = -1e30f, l0r = 0.f, l1r = 0.f;
; #pragma unroll
;     for (int d = 0; d < 4; ++d)
; #pragma unroll
;         for (int r = 0; r < 16; ++r) { O0[d][r] = 0.f; O1[d][r] = 0.f; }
;     u32x4 rk[2], rv[2];
;     attn_load1(u.kb, u.ld, 0, rk); attn_load1(u.vb, u.ld, 0, rv);
;     attn_store1(lds, A_KRS, rk); attn_store1(lds + A_KT, A_VRS, rv);
;     __syncthreads();
;     const int trq = (lane & 15) >> 2, trp = lane & 3, trblk = (lane >> 4) & 1;
;     const int v_rd = A_KT + (4 * hh + trq) * A_VRS + (16 * trblk + 4 * trp) * 2;
;     const int k_rd = l31 * A_KRS + hh * 16;
;     for (int t = 0; t < u.ntiles; ++t) {
;         const int cur = t & 1;
;         const bool more = t + 1 < u.ntiles;
;         const bool work = active && t < limit;
;         const unsigned char* kbase = lds + cur * A_BUF + k_rd;
;         const unsigned char* vbase = lds + cur * A_BUF + v_rd;
;         const bool mask_tail = (t == u.ntiles - 1) && (u.last_valid < 64);
;         unsigned char* nb = lds + (cur ^ 1) * A_BUF;
;         if (NS == 2) {
;             if (more) attn_load1(u.kb, u.ld, t + 1, rk);
.LBB0_1159:
	s_or_b64 exec, exec, s[12:13]
	v_add_u32_e32 v16, s14, v208
	v_mov_b32_e32 v17, s77
	v_sub_u32_e32 v18, s15, v217
	v_mov_b32_e32 v14, v181
	v_mov_b32_e32 v15, v181
	v_mov_b32_e32 v0, v181
	v_mov_b32_e32 v1, v181
	v_mov_b32_e32 v2, v181
	v_mov_b32_e32 v3, v181
	v_mov_b32_e32 v4, v181
	v_mov_b32_e32 v5, v181
	v_mov_b32_e32 v6, v181
	v_mov_b32_e32 v7, v181
	v_mov_b32_e32 v8, v181
	v_mov_b32_e32 v9, v181
	v_mov_b32_e32 v10, v181
	v_mov_b32_e32 v11, v181
	v_mov_b32_e32 v12, v181
	v_mov_b32_e32 v13, v181
	v_cndmask_b32_e64 v193, v16, v17, s[4:5]
	s_mov_b64 s[86:87], s[10:11]
	s_mov_b64 s[90:91], s[8:9]
	v_cmp_lt_u32_e64 s[8:9], 32, v18
	v_cmp_lt_u32_e64 s[10:11], 33, v18
	v_cmp_lt_u32_e64 s[12:13], 34, v18
	v_cmp_lt_u32_e64 s[14:15], 35, v18
	v_cmp_lt_u32_e64 s[16:17], 40, v18
	v_cmp_lt_u32_e64 s[18:19], 41, v18
	v_cmp_lt_u32_e64 s[20:21], 42, v18
	v_cmp_lt_u32_e64 s[22:23], 43, v18
	v_cmp_lt_u32_e64 s[24:25], 48, v18
	v_cmp_lt_u32_e64 s[26:27], 49, v18
	v_cmp_lt_u32_e64 s[28:29], 50, v18
	v_cmp_lt_u32_e64 s[30:31], 51, v18
	v_cmp_lt_u32_e64 s[34:35], 56, v18
	v_cmp_lt_u32_e64 s[36:37], 57, v18
	v_cmp_lt_u32_e64 s[38:39], 58, v18
	v_cmp_lt_u32_e64 s[40:41], 59, v18
	v_mov_b64_e32 v[46:47], v[14:15]
	v_mov_b64_e32 v[62:63], v[14:15]
	v_mov_b64_e32 v[78:79], v[14:15]
	v_mov_b64_e32 v[30:31], v[14:15]
	v_mov_b64_e32 v[94:95], v[14:15]
	v_mov_b64_e32 v[110:111], v[14:15]
	v_mov_b64_e32 v[126:127], v[14:15]
	v_add_u32_e32 v136, v212, v213
	s_add_i32 s61, s77, -1
	s_mov_b32 s42, 0
	v_mov_b32_e32 v228, 0xf149f2ca
	v_mov_b32_e32 v226, 0
	v_mov_b32_e32 v189, v177
	v_mov_b32_e32 v191, v175
	v_mov_b32_e32 v227, 0
	v_mov_b64_e32 v[44:45], v[12:13]
	v_mov_b64_e32 v[42:43], v[10:11]
	v_mov_b64_e32 v[40:41], v[8:9]
	v_mov_b64_e32 v[38:39], v[6:7]
	v_mov_b64_e32 v[36:37], v[4:5]
	v_mov_b64_e32 v[34:35], v[2:3]
	v_mov_b64_e32 v[32:33], v[0:1]
	v_mov_b64_e32 v[60:61], v[12:13]
	v_mov_b64_e32 v[58:59], v[10:11]
	v_mov_b64_e32 v[56:57], v[8:9]
	v_mov_b64_e32 v[54:55], v[6:7]
	v_mov_b64_e32 v[52:53], v[4:5]
	v_mov_b64_e32 v[50:51], v[2:3]
	v_mov_b64_e32 v[48:49], v[0:1]
	v_mov_b64_e32 v[76:77], v[12:13]
	v_mov_b64_e32 v[74:75], v[10:11]
	v_mov_b64_e32 v[72:73], v[8:9]
	v_mov_b64_e32 v[70:71], v[6:7]
	v_mov_b64_e32 v[68:69], v[4:5]
	v_mov_b64_e32 v[66:67], v[2:3]
	v_mov_b64_e32 v[64:65], v[0:1]
	v_mov_b64_e32 v[28:29], v[12:13]
	v_mov_b64_e32 v[26:27], v[10:11]
	v_mov_b64_e32 v[24:25], v[8:9]
	v_mov_b64_e32 v[22:23], v[6:7]
	v_mov_b64_e32 v[20:21], v[4:5]
	v_mov_b64_e32 v[18:19], v[2:3]
	v_mov_b64_e32 v[16:17], v[0:1]
	v_mov_b64_e32 v[92:93], v[12:13]
	v_mov_b64_e32 v[90:91], v[10:11]
	v_mov_b64_e32 v[88:89], v[8:9]
	v_mov_b64_e32 v[86:87], v[6:7]
	v_mov_b64_e32 v[84:85], v[4:5]
	v_mov_b64_e32 v[82:83], v[2:3]
	v_mov_b64_e32 v[80:81], v[0:1]
	v_mov_b64_e32 v[108:109], v[12:13]
	v_mov_b64_e32 v[106:107], v[10:11]
	v_mov_b64_e32 v[104:105], v[8:9]
	v_mov_b64_e32 v[102:103], v[6:7]
	v_mov_b64_e32 v[100:101], v[4:5]
	v_mov_b64_e32 v[98:99], v[2:3]
	v_mov_b64_e32 v[96:97], v[0:1]
	v_mov_b64_e32 v[124:125], v[12:13]
	v_mov_b64_e32 v[122:123], v[10:11]
	v_mov_b64_e32 v[120:121], v[8:9]
	v_mov_b64_e32 v[118:119], v[6:7]
	v_mov_b64_e32 v[116:117], v[4:5]
	v_mov_b64_e32 v[114:115], v[2:3]
	v_mov_b64_e32 v[112:113], v[0:1]
	v_mov_b32_e32 v229, 0xf149f2ca
	v_add_u32_e32 v137, v212, v214
	v_add_u32_e32 v138, v212, v215
	v_add_u32_e32 v139, v212, v216
	s_waitcnt vmcnt(3)
	ds_write_b128 v136, v[160:163]
	s_waitcnt vmcnt(2)
	ds_write_b128 v137, v[164:167]
	s_waitcnt vmcnt(1)
	ds_write_b128 v138, v[128:131] offset:17408
	s_waitcnt vmcnt(0)
	ds_write_b128 v139, v[132:135] offset:17408
	s_waitcnt lgkmcnt(0)
	s_barrier
.LBB0_1160:
	s_add_i32 s78, s42, 1
	s_cmp_lt_i32 s78, s77
	s_cselect_b64 s[64:65], -1, 0
	s_cmp_ge_i32 s78, s77
	s_cbranch_scc1 .LBB0_1162
	v_mad_u32_u24 v128, v189, s74, v180
	v_mad_u32_u24 v130, v191, s74, v180
	global_load_dwordx4 v[160:163], v128, s[86:87]
	global_load_dwordx4 v[164:167], v130, s[86:87]

; __device__ __forceinline__ void attn_load1(const bf16_t* __restrict__ src, int ld, int t, u32x4 (&r)[2]) {
;     const int tid = threadIdx.x;
; #pragma unroll
;     for (int i = 0; i < 2; ++i) {
;         const int c = tid + NTHR * i, key = c >> 4, ch = c & 15;
;         r[i] = *(const u32x4*)(src + (size_t)(t * 64 + key) * ld + ch * 8);
;     }
; }
; __device__ __forceinline__ void attn_store1(unsigned char* buf, int rs, const u32x4 (&r)[2]) {
;     const int tid = threadIdx.x;
; #pragma unroll
;     for (int i = 0; i < 2; ++i) {
;         const int c = tid + NTHR * i, key = c >> 4, ch = c & 15;
;         *(u32x4*)(buf + key * rs + ch * 16) = r[i];
;     }
; }
; template <int NS>
; __device__ __forceinline__ void attn_unit(const AUnit& u, unsigned char* lds, const bf16_t* __restrict__ GT, bf16_t* BRc, float sc, float lam, const float* __restrict__ subln) {
;     ...
;             if (more) { attn_store1(nb, A_KRS, rk); attn_load1(u.vb, u.ld, t + 1, rk); }
;             if (work) attn_stream<NS, 1>(kbase, vbase, q_rd, mask_tail, u.last_valid, hh, sc, O1, m1, l1r);
.LBB0_1174:
	v_add_u32_e32 v128, v231, v213
	s_waitcnt vmcnt(1)
	ds_write_b128 v128, v[160:163]
	v_add_u32_e32 v128, v231, v214
	s_waitcnt vmcnt(0)
	ds_write_b128 v128, v[164:167]
	v_mad_u32_u24 v128, v189, s74, v180
	v_mad_u32_u24 v130, v191, s74, v180
	global_load_dwordx4 v[160:163], v128, s[90:91]
	global_load_dwordx4 v[164:167], v130, s[90:91]
	s_and_saveexec_b64 s[64:65], s[62:63]
	s_cbranch_execz .LBB0_1170
